# hg_item(true) steps 2/3: ds_read->wait->mfma chains software-pipelined with 4 rotating fragment sets in spare VGPRs (same accumulation order, bit-identical)
# speedup vs baseline: 1.0126x; 1.0013x over previous
; #define LAS __attribute__((address_space(3)))
; template <bool FULL, bool STORE = true>
; __device__ __forceinline__ void hg_item(const Prm& P, LAS unsigned char* lds, int item, int wave) {
;     ...
;             { const int tb = wave >> 2, vb = wave & 3; f32x16 o;
; #pragma unroll
;                 for (int r = 0; r < 16; ++r) o[r] = 0.f;
; #pragma unroll
;                 for (int ks = 0; ks < 4; ++ks) { if (ks < 2 || tb) { const bf16x8 a = *(const LAS bf16x8*)(lds + HL_PP + (tb * 32 + l31) * 144 + ks * 32 + lh * 16), bb = *(const LAS bf16x8*)(lds + HL_IVT + (vb * 32 + l31) * 144 + ks * 32 + lh * 16);
;                         o = __builtin_amdgcn_mfma_f32_32x32x16_bf16(a, bb, o, 0, 0, 0); } }
; #pragma unroll
;                 for (int ks = 0; ks < 8; ++ks) { const bf16x8 a = *(const LAS bf16x8*)(lds + HL_QD + (tb * 32 + l31) * 272 + ks * 32 + lh * 16), bb = *(const LAS bf16x8*)(lds + HL_ST + (vb * 32 + l31) * 272 + ks * 32 + lh * 16);
;                     o = __builtin_amdgcn_mfma_f32_32x32x16_bf16(a, bb, o, 0, 0, 0); }
; #pragma unroll
;                 for (int r = 0; r < 16; ++r) { const int t = tb * 32 + (r & 3) + 8 * (r >> 2) + 4 * lh; *(LAS float*)(lds + HL_OS + t * 528 + (vb * 32 + l31) * 4) = o[r]; }
;             }
;         }
; #pragma unroll
;         for (int g4 = 0; g4 < 4; ++g4) { const f32x4 d = *(const LAS f32x4*)(lds + HL_DC + (kb * 32 + 8 * g4 + 4 * lh) * 4);
; #pragma unroll
;             for (int i = 0; i < 2; ++i)
; #pragma unroll
;                 for (int j = 0; j < 4; ++j) S[i][4 * g4 + j] *= d[j]; }
; #pragma unroll
;         for (int ks = 0; ks < 4; ++ks) { const bf16x8 a = *(const LAS bf16x8*)(lds + HL_KDT + (kb * 32 + l31) * 144 + ks * 32 + lh * 16);
; #pragma unroll
;             for (int i = 0; i < 2; ++i) { const bf16x8 bb = *(const LAS bf16x8*)(lds + HL_IVT + ((vb0 + i) * 32 + l31) * 144 + ks * 32 + lh * 16); S[i] = __builtin_amdgcn_mfma_f32_32x32x16_bf16(a, bb, S[i], 0, 0, 0); } }
.LBB0_839:
	s_mov_b32 s33, 0x800000
	s_add_u32 s86, s86, 0x20000
	s_addc_u32 s87, s87, 0
	v_lshlrev_b32_e32 v104, 16, v52
	v_and_b32_e32 v105, 0xffff0000, v52
	v_lshlrev_b32_e32 v52, 16, v53
	v_and_b32_e32 v53, 0xffff0000, v53
	s_add_u32 s84, s84, 0x10000
	s_addc_u32 s85, s85, 0
	s_cmp_lg_u32 s86, 0x200000
	s_waitcnt lgkmcnt(6)
	v_mfma_f32_32x32x16_bf16 v[32:47], v[172:175], v[176:179], v[32:47]
	ds_read_b128 v[172:175], v151 offset:34944
	ds_read_b128 v[176:179], v152 offset:128
	s_waitcnt lgkmcnt(6)
	v_mfma_f32_32x32x16_bf16 v[32:47], v[180:183], v[184:187], v[32:47]
	ds_read_b128 v[180:183], v151 offset:34976
	ds_read_b128 v[184:187], v152 offset:160
	s_waitcnt lgkmcnt(6)
	v_mfma_f32_32x32x16_bf16 v[32:47], v[188:191], v[192:195], v[32:47]
	ds_read_b128 v[188:191], v151 offset:35008
	ds_read_b128 v[192:195], v152 offset:192
	s_waitcnt lgkmcnt(6)
	v_mfma_f32_32x32x16_bf16 v[32:47], v[196:199], v[200:203], v[32:47]
	ds_read_b128 v[196:199], v151 offset:35040
	ds_read_b128 v[200:203], v152 offset:224
	s_waitcnt lgkmcnt(6)
	v_mfma_f32_32x32x16_bf16 v[32:47], v[172:175], v[176:179], v[32:47]
	s_waitcnt lgkmcnt(4)
	v_mfma_f32_32x32x16_bf16 v[32:47], v[180:183], v[184:187], v[32:47]
	s_waitcnt lgkmcnt(2)
	v_mfma_f32_32x32x16_bf16 v[32:47], v[188:191], v[192:195], v[32:47]
	s_waitcnt lgkmcnt(0)
	v_mfma_f32_32x32x16_bf16 v[32:47], v[196:199], v[200:203], v[32:47]
	s_nop 11
	ds_write2_b32 v153, v32, v33 offset1:132
	v_add_u32_e32 v32, 0x400, v153
	ds_write2_b32 v32, v34, v35 offset0:8 offset1:140
	v_add_u32_e32 v32, 0x1000, v153
	ds_write2_b32 v32, v36, v37 offset0:32 offset1:164
	v_add_u32_e32 v32, 0x1400, v153
	ds_write2_b32 v32, v38, v39 offset0:40 offset1:172
	v_add_u32_e32 v32, 0x2000, v153
	ds_write2_b32 v32, v40, v41 offset0:64 offset1:196
	v_add_u32_e32 v32, 0x2400, v153
	ds_write2_b32 v32, v42, v43 offset0:72 offset1:204
	v_add_u32_e32 v32, 0x3000, v153
	ds_write2_b32 v32, v44, v45 offset0:96 offset1:228
	v_add_u32_e32 v32, 0x3400, v153
	ds_write2_b32 v32, v46, v47 offset0:104 offset1:236
	v_add_u32_e32 v40, s96, v128
	ds_read_b128 v[32:35], v40
	ds_read_b128 v[36:39], v40 offset:32
	s_waitcnt lgkmcnt(1)
	v_pk_mul_f32 v[0:1], v[0:1], v[32:33]
	v_pk_mul_f32 v[2:3], v[2:3], v[34:35]
	v_pk_mul_f32 v[16:17], v[16:17], v[32:33]
	v_pk_mul_f32 v[18:19], v[18:19], v[34:35]
	ds_read_b128 v[32:35], v40 offset:64
	s_waitcnt lgkmcnt(1)
	v_pk_mul_f32 v[4:5], v[4:5], v[36:37]
	v_pk_mul_f32 v[6:7], v[6:7], v[38:39]
	v_pk_mul_f32 v[20:21], v[20:21], v[36:37]
	v_pk_mul_f32 v[22:23], v[22:23], v[38:39]
	s_waitcnt lgkmcnt(0)
	v_pk_mul_f32 v[8:9], v[8:9], v[32:33]
	v_pk_mul_f32 v[10:11], v[10:11], v[34:35]
	v_pk_mul_f32 v[24:25], v[24:25], v[32:33]
	v_pk_mul_f32 v[26:27], v[26:27], v[34:35]
	ds_read_b128 v[32:35], v40 offset:96
	s_waitcnt lgkmcnt(0)
	v_pk_mul_f32 v[12:13], v[12:13], v[32:33]
	v_pk_mul_f32 v[14:15], v[14:15], v[34:35]
	v_pk_mul_f32 v[28:29], v[28:29], v[32:33]
	v_pk_mul_f32 v[30:31], v[30:31], v[34:35]
	ds_read_b128 v[32:35], v154 offset:52224
	ds_read_b128 v[36:39], v154 offset:52256
	ds_read_b128 v[40:43], v155
	ds_read_b128 v[44:47], v155 offset:32
	s_waitcnt lgkmcnt(1)
	v_mfma_f32_32x32x16_bf16 v[0:15], v[32:35], v[40:43], v[0:15]
	ds_read_b128 v[40:43], v155 offset:4608
	s_waitcnt lgkmcnt(0)
	v_mfma_f32_32x32x16_bf16 v[16:31], v[32:35], v[40:43], v[16:31]
	ds_read_b128 v[32:35], v155 offset:4640
	v_mfma_f32_32x32x16_bf16 v[0:15], v[36:39], v[44:47], v[0:15]
	s_waitcnt lgkmcnt(0)
	v_mfma_f32_32x32x16_bf16 v[16:31], v[36:39], v[32:35], v[16:31]
	ds_read_b128 v[32:35], v154 offset:52288
	ds_read_b128 v[36:39], v155 offset:64
	s_waitcnt lgkmcnt(0)
	v_mfma_f32_32x32x16_bf16 v[0:15], v[32:35], v[36:39], v[0:15]
	ds_read_b128 v[36:39], v155 offset:4672
	s_waitcnt lgkmcnt(0)
	v_mfma_f32_32x32x16_bf16 v[16:31], v[32:35], v[36:39], v[16:31]
	ds_read_b128 v[32:35], v154 offset:52320
	ds_read_b128 v[36:39], v155 offset:96
	s_waitcnt lgkmcnt(0)
	v_mfma_f32_32x32x16_bf16 v[0:15], v[32:35], v[36:39], v[0:15]
	ds_read_b128 v[36:39], v155 offset:4704
	s_waitcnt lgkmcnt(0)
	s_barrier
; #define LAS __attribute__((address_space(3)))
; __device__ __forceinline__ unsigned pk2(float lo, float hi) { typedef float f2v __attribute__((ext_vector_type(2))); typedef __bf16 b2v __attribute__((ext_vector_type(2))); const f2v v = {lo, hi}; const b2v b = __builtin_convertvector(v, b2v); return __builtin_bit_cast(unsigned, b); }
; __device__ __forceinline__ u32x4 pack8(const float (&f)[8]) { u32x4 w; w.x = pk2(f[0], f[1]); w.y = pk2(f[2], f[3]); w.z = pk2(f[4], f[5]); w.w = pk2(f[6], f[7]); return w; }
; template <bool FULL, bool STORE = true>
; __device__ __forceinline__ void hg_item(const Prm& P, LAS unsigned char* lds, int item, int wave) {
;     ...
;         if (FULL) {
;             __syncthreads();
; #pragma unroll
;             for (int i = 0; i < 2; ++i)
; #pragma unroll
;                 for (int g4 = 0; g4 < 4; ++g4) { u32x2 w; w.x = pk2(S[i][4 * g4], S[i][4 * g4 + 1]); w.y = pk2(S[i][4 * g4 + 2], S[i][4 * g4 + 3]);
;                     *(LAS u32x2*)(lds + HL_ST + ((vb0 + i) * 32 + l31) * 272 + (kb * 32 + 8 * g4 + 4 * lh) * 2) = w; }
;             { const int t = tid >> 3, vs = (tid & 7) * 16; float o[16]; float ss = 0.f;
; #pragma unroll
;                 for (int q4 = 0; q4 < 4; ++q4) { const f32x4 x4 = *(const LAS f32x4*)(lds + HL_OS + t * 528 + (vs + 4 * q4) * 4);
; #pragma unroll
;                     for (int j = 0; j < 4; ++j) { o[4 * q4 + j] = x4[j]; ss += x4[j] * x4[j]; } }
;                 ss += __shfl_xor(ss, 1); ss += __shfl_xor(ss, 2); ss += __shfl_xor(ss, 4);
;                 const float r = rsqrtf(ss * (1.0f / 128.0f) + EPS);
;                 const size_t oo = (row0 + t) * 1024 + h * 128 + vs; const float* gn = P.in[I_HGNG] + h * 128 + vs;
;                 float g0[8], g1[8]; unpack8(gcur0, g0); unpack8(gcur1, g1);
;                 float w0[8], w1[8];
; #pragma unroll
;                 for (int j = 0; j < 8; ++j) { w0[j] = o[j] * r * gn[j] * g0[j]; w1[j] = o[8 + j] * r * gn[8 + j] * g1[j]; }
;                 if (STORE) { *(u32x4*)(AHG + oo) = pack8(w0); *(u32x4*)(AHG + oo + 8) = pack8(w1); }
	v_mfma_f32_32x32x16_bf16 v[16:31], v[32:35], v[36:39], v[16:31]
	s_nop 7
	v_cvt_pk_bf16_f32 v32, v0, v1
	v_cvt_pk_bf16_f32 v33, v2, v3
	v_cvt_pk_bf16_f32 v34, v4, v5
	v_cvt_pk_bf16_f32 v35, v6, v7
	ds_write2_b64 v156, v[32:33], v[34:35] offset1:2
	v_cvt_pk_bf16_f32 v32, v8, v9
	v_cvt_pk_bf16_f32 v33, v10, v11
	v_cvt_pk_bf16_f32 v34, v12, v13
	v_cvt_pk_bf16_f32 v35, v14, v15
	ds_write2_b64 v156, v[32:33], v[34:35] offset0:4 offset1:6
	v_cvt_pk_bf16_f32 v32, v16, v17
	v_cvt_pk_bf16_f32 v33, v18, v19
	v_cvt_pk_bf16_f32 v34, v20, v21
	v_cvt_pk_bf16_f32 v35, v22, v23
	v_add_u32_e32 v36, 0x2000, v156
	ds_write2_b64 v36, v[32:33], v[34:35] offset0:64 offset1:66
	v_cvt_pk_bf16_f32 v32, v24, v25
	v_cvt_pk_bf16_f32 v33, v26, v27
	v_cvt_pk_bf16_f32 v34, v28, v29
	v_cvt_pk_bf16_f32 v35, v30, v31
	ds_write2_b64 v36, v[32:33], v[34:35] offset0:68 offset1:70
	ds_read_b128 v[66:69], v157
	ds_read_b128 v[36:39], v157 offset:16
	ds_read_b128 v[44:47], v157 offset:32
	ds_read_b128 v[32:35], v157 offset:48
	s_waitcnt lgkmcnt(3)
	v_mul_f32_e32 v64, v67, v67
	v_fmac_f32_e32 v64, v66, v66
	v_fmac_f32_e32 v64, v68, v68
	v_fmac_f32_e32 v64, v69, v69
	s_waitcnt lgkmcnt(2)
	v_fmac_f32_e32 v64, v36, v36
	v_fmac_f32_e32 v64, v37, v37
	v_fmac_f32_e32 v64, v38, v38
	v_fmac_f32_e32 v64, v39, v39
	s_waitcnt lgkmcnt(1)
	v_pk_mul_f32 v[42:43], v[44:45], v[44:45]
	v_pk_mul_f32 v[40:41], v[46:47], v[46:47]
	v_add_f32_e32 v42, v42, v64
	v_add_f32_e32 v42, v43, v42
	v_add_f32_e32 v40, v40, v42
	v_add_f32_e32 v64, v41, v40
	s_waitcnt lgkmcnt(0)
	v_pk_mul_f32 v[42:43], v[32:33], v[32:33]
	v_pk_mul_f32 v[40:41], v[34:35], v[34:35]
	v_add_f32_e32 v42, v42, v64
	v_add_f32_e32 v42, v43, v42
	v_add_f32_e32 v40, v40, v42
	v_add_f32_e32 v40, v41, v40
	ds_bpermute_b32 v41, v129, v40
	s_waitcnt lgkmcnt(0)
	v_add_f32_e32 v40, v40, v41
	ds_bpermute_b32 v41, v130, v40
	s_waitcnt lgkmcnt(0)
	v_add_f32_e32 v40, v40, v41
	ds_bpermute_b32 v41, v131, v40
	s_waitcnt lgkmcnt(0)
	v_add_f32_e32 v40, v40, v41
	v_fmamk_f32 v40, v40, 0x3c000000, v109
	v_cmp_gt_f32_e32 vcc, s33, v40
	v_mul_f32_e32 v41, 0x4b800000, v40
	s_mov_b32 s33, 0x7400000
	v_cndmask_b32_e32 v40, v40, v41, vcc
	v_rsq_f32_e32 v40, v40
	s_nop 0
	v_mul_f32_e32 v41, 0x45800000, v40
	v_cndmask_b32_e32 v74, v40, v41, vcc
	v_pk_mul_f32 v[106:107], v[66:67], v[74:75] op_sel_hi:[1,0]
	v_pk_mul_f32 v[46:47], v[46:47], v[74:75] op_sel_hi:[1,0]
	v_pk_mul_f32 v[36:37], v[36:37], v[74:75] op_sel_hi:[1,0]
	v_pk_mul_f32 v[32:33], v[32:33], v[74:75] op_sel_hi:[1,0]
	v_pk_mul_f32 v[44:45], v[44:45], v[74:75] op_sel_hi:[1,0]
	v_pk_mul_f32 v[38:39], v[38:39], v[74:75] op_sel_hi:[1,0]
	v_pk_mul_f32 v[34:35], v[34:35], v[74:75] op_sel_hi:[1,0]
	s_waitcnt vmcnt(0)
	v_pk_mul_f32 v[32:33], v[224:225], v[32:33]
	v_pk_mul_f32 v[46:47], v[230:231], v[46:47]
	v_pk_mul_f32 v[36:37], v[232:233], v[36:37]
	v_pk_mul_f32 v[106:107], v[236:237], v[106:107]
	v_pk_mul_f32 v[44:45], v[228:229], v[44:45]
	v_pk_mul_f32 v[104:105], v[106:107], v[104:105]
	v_lshlrev_b32_e32 v106, 16, v48
	v_and_b32_e32 v107, 0xffff0000, v48
	v_lshlrev_b32_e32 v48, 16, v49
	v_and_b32_e32 v49, 0xffff0000, v49
	v_pk_mul_f32 v[46:47], v[46:47], v[48:49]
	v_lshlrev_b32_e32 v48, 16, v54
	v_and_b32_e32 v49, 0xffff0000, v54
	v_pk_mul_f32 v[36:37], v[36:37], v[48:49]
	v_lshlrev_b32_e32 v48, 16, v50
	v_and_b32_e32 v49, 0xffff0000, v50
	v_pk_mul_f32 v[64:65], v[68:69], v[74:75] op_sel_hi:[1,0]
	v_pk_mul_f32 v[40:41], v[32:33], v[48:49]
	v_lshlrev_b32_e32 v32, 16, v55
	v_and_b32_e32 v33, 0xffff0000, v55
	v_pk_mul_f32 v[38:39], v[234:235], v[38:39]
	v_pk_mul_f32 v[64:65], v[238:239], v[64:65]
	v_pk_mul_f32 v[38:39], v[38:39], v[32:33]
	v_lshlrev_b32_e32 v32, 16, v51
	v_and_b32_e32 v33, 0xffff0000, v51
	v_pk_mul_f32 v[34:35], v[226:227], v[34:35]
	v_pk_mul_f32 v[52:53], v[64:65], v[52:53]
	v_pk_mul_f32 v[42:43], v[34:35], v[32:33]
	v_cvt_pk_bf16_f32 v34, v36, v37
	v_add_co_u32_e32 v36, vcc, s33, v102
	v_pk_mul_f32 v[44:45], v[44:45], v[106:107]
	v_cvt_pk_bf16_f32 v32, v104, v105
	v_cvt_pk_bf16_f32 v33, v52, v53
	v_cvt_pk_bf16_f32 v35, v38, v39
	v_addc_co_u32_e32 v37, vcc, 0, v103, vcc
	v_mov_b64_e32 v[52:53], v[56:57]
	v_mov_b64_e32 v[48:49], v[60:61]
	global_store_dwordx4 v[36:37], v[32:35], off
	v_mov_b64_e32 v[54:55], v[58:59]
	v_mov_b64_e32 v[50:51], v[62:63]
	v_cvt_pk_bf16_f32 v32, v44, v45
	v_cvt_pk_bf16_f32 v33, v46, v47
	v_cvt_pk_bf16_f32 v34, v40, v41
	v_cvt_pk_bf16_f32 v35, v42, v43
	global_store_dwordx4 v[36:37], v[32:35], off offset:16
	v_cvt_f32_f16_e32 v78, v240
	v_cvt_f32_f16_sdwa v79, v240 dst_sel:DWORD dst_unused:UNUSED_PAD src0_sel:WORD_1
	v_cvt_f32_f16_e32 v80, v241
	v_cvt_f32_f16_sdwa v81, v241 dst_sel:DWORD dst_unused:UNUSED_PAD src0_sel:WORD_1
	v_cvt_f32_f16_e32 v82, v242
	v_cvt_f32_f16_sdwa v83, v242 dst_sel:DWORD dst_unused:UNUSED_PAD src0_sel:WORD_1
	v_cvt_f32_f16_e32 v84, v243
	v_cvt_f32_f16_sdwa v85, v243 dst_sel:DWORD dst_unused:UNUSED_PAD src0_sel:WORD_1
	v_cvt_f32_f16_e32 v86, v244
	v_cvt_f32_f16_sdwa v87, v244 dst_sel:DWORD dst_unused:UNUSED_PAD src0_sel:WORD_1
	v_cvt_f32_f16_e32 v88, v245
	v_cvt_f32_f16_sdwa v89, v245 dst_sel:DWORD dst_unused:UNUSED_PAD src0_sel:WORD_1
	v_cvt_f32_f16_e32 v90, v246
	v_cvt_f32_f16_sdwa v91, v246 dst_sel:DWORD dst_unused:UNUSED_PAD src0_sel:WORD_1
	v_cvt_f32_f16_e32 v92, v247
	v_cvt_f32_f16_sdwa v93, v247 dst_sel:DWORD dst_unused:UNUSED_PAD src0_sel:WORD_1
	s_cbranch_scc0 .LBB0_821

; #define LAS __attribute__((address_space(3)))
; __device__ __forceinline__ unsigned f2bf(float f) { unsigned u = __builtin_bit_cast(unsigned, f); return (u + 0x7fffu + ((u >> 16) & 1u)) >> 16; }
; template <bool FULL, bool STORE = true>
; __device__ __forceinline__ void hg_item(const Prm& P, LAS unsigned char* lds, int item, int wave) {
;     ...
;             if (wave < 3) { const int tb = wave ? 1 : 0, sb = wave == 2 ? 1 : 0; f32x16 sc;
; #pragma unroll
;                 for (int r = 0; r < 16; ++r) sc[r] = 0.f;
; #pragma unroll
;                 for (int ks = 0; ks < 8; ++ks) { const bf16x8 a = *(const LAS bf16x8*)(lds + HL_QM + (tb * 32 + l31) * 272 + ks * 32 + lh * 16), bb = *(const LAS bf16x8*)(lds + HL_KM + (sb * 32 + l31) * 272 + ks * 32 + lh * 16);
;                     sc = __builtin_amdgcn_mfma_f32_32x32x16_bf16(a, bb, sc, 0, 0, 0); }
; #pragma unroll
;                 for (int r = 0; r < 16; ++r) { const int t = tb * 32 + (r & 3) + 8 * (r >> 2) + 4 * lh, s = sb * 32 + l31; *(LAS bf16_t*)(lds + HL_PP + t * 144 + s * 2) = (bf16_t)f2bf(s <= t ? sc[r] : 0.f); }
;             }
;             __syncthreads();
;             { const int tb = wave >> 2, vb = wave & 3; f32x16 o;
; #pragma unroll
;                 for (int r = 0; r < 16; ++r) o[r] = 0.f;
; #pragma unroll
;                 for (int ks = 0; ks < 4; ++ks) { if (ks < 2 || tb) { const bf16x8 a = *(const LAS bf16x8*)(lds + HL_PP + (tb * 32 + l31) * 144 + ks * 32 + lh * 16), bb = *(const LAS bf16x8*)(lds + HL_IVT + (vb * 32 + l31) * 144 + ks * 32 + lh * 16);
;                         o = __builtin_amdgcn_mfma_f32_32x32x16_bf16(a, bb, o, 0, 0, 0); } }
; #pragma unroll
;                 for (int ks = 0; ks < 8; ++ks) { const bf16x8 a = *(const LAS bf16x8*)(lds + HL_QD + (tb * 32 + l31) * 272 + ks * 32 + lh * 16), bb = *(const LAS bf16x8*)(lds + HL_ST + (vb * 32 + l31) * 272 + ks * 32 + lh * 16);
;                     o = __builtin_amdgcn_mfma_f32_32x32x16_bf16(a, bb, o, 0, 0, 0); }
.LBB0_844:
	s_andn2_b64 vcc, exec, s[76:77]
	s_waitcnt lgkmcnt(0)
	s_barrier
	s_cbranch_vccnz .LBB0_846
	ds_read_b128 v[172:175], v133
	ds_read_b128 v[176:179], v134 offset:17408
	ds_read_b128 v[180:183], v133 offset:32
	ds_read_b128 v[184:187], v134 offset:17440
	ds_read_b128 v[188:191], v133 offset:64
	ds_read_b128 v[192:195], v134 offset:17472
	ds_read_b128 v[196:199], v133 offset:96
	ds_read_b128 v[200:203], v134 offset:17504
	s_waitcnt lgkmcnt(6)
	v_mfma_f32_32x32x16_bf16 v[32:47], v[172:175], v[176:179], 0
	ds_read_b128 v[172:175], v133 offset:128
	ds_read_b128 v[176:179], v134 offset:17536
	s_waitcnt lgkmcnt(6)
	v_mfma_f32_32x32x16_bf16 v[32:47], v[180:183], v[184:187], v[32:47]
	ds_read_b128 v[180:183], v133 offset:160
	ds_read_b128 v[184:187], v134 offset:17568
	s_waitcnt lgkmcnt(6)
	v_mfma_f32_32x32x16_bf16 v[32:47], v[188:191], v[192:195], v[32:47]
	ds_read_b128 v[188:191], v133 offset:192
	ds_read_b128 v[192:195], v134 offset:17600
	s_waitcnt lgkmcnt(6)
	v_mfma_f32_32x32x16_bf16 v[32:47], v[196:199], v[200:203], v[32:47]
	ds_read_b128 v[196:199], v133 offset:224
	ds_read_b128 v[200:203], v134 offset:17632
	s_waitcnt lgkmcnt(6)
	v_mfma_f32_32x32x16_bf16 v[32:47], v[172:175], v[176:179], v[32:47]
	s_waitcnt lgkmcnt(4)
	v_mfma_f32_32x32x16_bf16 v[32:47], v[180:183], v[184:187], v[32:47]
	s_waitcnt lgkmcnt(2)
	v_mfma_f32_32x32x16_bf16 v[32:47], v[188:191], v[192:195], v[32:47]
	s_waitcnt lgkmcnt(0)
	v_mfma_f32_32x32x16_bf16 v[32:47], v[196:199], v[200:203], v[32:47]
	s_nop 11
	v_cndmask_b32_e64 v32, v32, 0, s[18:19]
	v_cndmask_b32_e64 v33, v33, 0, s[20:21]
	v_cndmask_b32_e64 v34, v34, 0, s[22:23]
	v_cndmask_b32_e64 v35, v35, 0, s[24:25]
	v_cndmask_b32_e64 v36, v36, 0, s[26:27]
	v_cndmask_b32_e64 v37, v37, 0, s[28:29]
	v_cndmask_b32_e64 v38, v38, 0, s[30:31]
	v_cndmask_b32_e64 v39, v39, 0, s[34:35]
	v_cndmask_b32_e64 v40, v40, 0, s[36:37]
	v_cndmask_b32_e64 v41, v41, 0, s[38:39]
	v_cndmask_b32_e64 v42, v42, 0, s[40:41]
	v_cndmask_b32_e64 v43, v43, 0, s[42:43]
	v_cndmask_b32_e64 v44, v44, 0, s[44:45]
	v_bfe_u32 v64, v32, 16, 1
	v_cndmask_b32_e64 v45, v45, 0, s[46:47]
	v_bfe_u32 v65, v33, 16, 1
	v_bfe_u32 v66, v34, 16, 1
	v_bfe_u32 v67, v35, 16, 1
	v_bfe_u32 v68, v36, 16, 1
	v_bfe_u32 v69, v37, 16, 1
	v_bfe_u32 v70, v38, 16, 1
	v_bfe_u32 v71, v39, 16, 1
	v_bfe_u32 v72, v40, 16, 1
	v_bfe_u32 v73, v41, 16, 1
	v_bfe_u32 v74, v42, 16, 1
	v_bfe_u32 v104, v43, 16, 1
	v_bfe_u32 v105, v44, 16, 1
	v_add3_u32 v32, v32, v64, s95
	v_add3_u32 v33, v33, v65, s95
	v_add3_u32 v34, v34, v66, s95
	v_add3_u32 v35, v35, v67, s95
	v_add3_u32 v36, v36, v68, s95
	v_add3_u32 v37, v37, v69, s95
	v_add3_u32 v38, v38, v70, s95
	v_add3_u32 v39, v39, v71, s95
	v_add3_u32 v40, v40, v72, s95
	v_add3_u32 v41, v41, v73, s95
	v_add3_u32 v42, v42, v74, s95
	v_add3_u32 v43, v43, v104, s95
	v_add3_u32 v44, v44, v105, s95
	ds_write_b16_d16_hi v135, v32
	ds_write_b16_d16_hi v136, v33
	ds_write_b16_d16_hi v137, v34
	ds_write_b16_d16_hi v138, v35
	ds_write_b16_d16_hi v139, v36
	ds_write_b16_d16_hi v140, v37
	ds_write_b16_d16_hi v141, v38
	ds_write_b16_d16_hi v142, v39
	ds_write_b16_d16_hi v143, v40
	ds_write_b16_d16_hi v144, v41
	ds_write_b16_d16_hi v145, v42
	ds_write_b16_d16_hi v146, v43
	ds_write_b16_d16_hi v147, v44
	v_bfe_u32 v32, v45, 16, 1
	v_add3_u32 v32, v45, v32, s95
	ds_write_b16_d16_hi v148, v32
	v_cndmask_b32_e64 v32, v46, 0, s[48:49]
	v_bfe_u32 v33, v32, 16, 1
	v_add3_u32 v32, v32, v33, s95
	ds_write_b16_d16_hi v149, v32
	v_cndmask_b32_e64 v32, v47, 0, s[50:51]
	v_bfe_u32 v33, v32, 16, 1
	v_add3_u32 v32, v32, v33, s95
	ds_write_b16_d16_hi v150, v32
.LBB0_846:
	s_waitcnt lgkmcnt(0)
	s_barrier
	ds_read_b128 v[204:207], v158
	ds_read_b128 v[208:211], v159
	ds_read_b128 v[212:215], v158 offset:32
	ds_read_b128 v[216:219], v159 offset:32
	s_andn2_b64 vcc, exec, s[4:5]
	s_cbranch_vccnz .Lhgt_tb0
	ds_read_b128 v[188:191], v158 offset:64
	ds_read_b128 v[192:195], v159 offset:64
	ds_read_b128 v[196:199], v158 offset:96
	ds_read_b128 v[200:203], v159 offset:96
	ds_read_b128 v[172:175], v151 offset:34816
	ds_read_b128 v[176:179], v152
	ds_read_b128 v[180:183], v151 offset:34848
	ds_read_b128 v[184:187], v152 offset:32
	s_waitcnt lgkmcnt(10)
	v_mfma_f32_32x32x16_bf16 v[32:47], v[204:207], v[208:211], 0
	s_waitcnt lgkmcnt(8)
	v_mfma_f32_32x32x16_bf16 v[32:47], v[212:215], v[216:219], v[32:47]
	s_waitcnt lgkmcnt(6)
	v_mfma_f32_32x32x16_bf16 v[32:47], v[188:191], v[192:195], v[32:47]
	ds_read_b128 v[188:191], v151 offset:34880
	ds_read_b128 v[192:195], v152 offset:64
	s_waitcnt lgkmcnt(6)
	v_mfma_f32_32x32x16_bf16 v[32:47], v[196:199], v[200:203], v[32:47]
	ds_read_b128 v[196:199], v151 offset:34912
	ds_read_b128 v[200:203], v152 offset:96
	s_branch .LBB0_839
.Lhgt_tb0:
	ds_read_b128 v[172:175], v151 offset:34816
	ds_read_b128 v[176:179], v152
	ds_read_b128 v[180:183], v151 offset:34848
	ds_read_b128 v[184:187], v152 offset:32
	ds_read_b128 v[188:191], v151 offset:34880
	ds_read_b128 v[192:195], v152 offset:64
	s_waitcnt lgkmcnt(8)
	v_mfma_f32_32x32x16_bf16 v[32:47], v[204:207], v[208:211], 0
	s_waitcnt lgkmcnt(6)
	v_mfma_f32_32x32x16_bf16 v[32:47], v[212:215], v[216:219], v[32:47]
	ds_read_b128 v[196:199], v151 offset:34912
	ds_read_b128 v[200:203], v152 offset:96
	s_branch .LBB0_839
